# P1: first K-loop body after a plain (store-only) epilogue waits with vmcnt(24) so the 16 Z stores drain under two more phases (same DMA loads forced)
# speedup vs baseline: 1.0018x; 1.0018x over previous
; #define PG8_STAGE(bufoff, gbase, voff) do { _Pragma("unroll") for (int _i = 0; _i < 2; ++_i) \
;         __builtin_amdgcn_global_load_lds((const unsigned*)((const char*)(gbase) + (voff)[_i]), (LAS unsigned*)(lds + (bufoff) + ldsw + _i * 8192), 16, 0, 0); } while (0)
; #define PG8_WAIT_V(n) asm volatile("s_waitcnt vmcnt(" #n ")" ::: "memory")
; #define PG8_BAR __builtin_amdgcn_s_barrier()
; template <class Epi, bool HOOK = false>
; DI void gemm_phase(LAS unsigned char* lds, const Gemm g, const StaticOrder& S, const Epi& E) {
;     int tid = threadIdx.x; asm volatile("" : "+v"(tid));
;     const int wid = __builtin_amdgcn_readfirstlane(tid >> 6), lane = tid & 63, wr = wid >> 2, wc = wid & 3, fr = lane & 15, fq = lane >> 4;
;     const int K = g.K, nt = K / BK;
;     unsigned voffA[2], voffB[2];
; #pragma unroll
;     for (int i = 0; i < 2; ++i) { int R, C; stage_rc(tid * 16 + i * 8192, R, C); const int Rb = (R & ~31) + perm32(R & 31);
;         voffA[i] = (unsigned)(R * K + C) * 2u; voffB[i] = (unsigned)(Rb * K + C) * 2u; }
;     const size_t kstep = (size_t)(BK * 2);
;     const size_t hstep = (size_t)HALF * K * 2;
;     const size_t tstep = 2 * hstep;
;     const unsigned ldsw = (unsigned)wid * 1024u;
;     const int aoff = lds_byte(wr * 64 + fr, fq * 8), boff = lds_byte(wc * 32 + fr, fq * 8);
;     ...
;     Unit cur, nxt; int ui = 0;
;     if (!S.next(0, cur)) return;
;     f32x4 acc[2][2][4][2];
; #pragma unroll
;     for (int a = 0; a < 2; ++a)
; #pragma unroll
;         for (int b = 0; b < 2; ++b)
; #pragma unroll
;             for (int m = 0; m < 4; ++m)
; #pragma unroll
;                 for (int n = 0; n < 2; ++n) acc[a][b][m][n] = (f32x4){0.f, 0.f, 0.f, 0.f};
;     bf16x8 At[4][2], B0[2][2], B1[2][2];
;     const char* cA = (const char*)g.A + (size_t)cur.pm * tstep; const char* cB = (const char*)g.Bt + (size_t)cur.pn * tstep;
;     PG8_STAGE(PG8_SB(0, 0), cB, voffB); PG8_STAGE(PG8_SB(0, 1), cB + hstep, voffB); PG8_STAGE(PG8_SA(0, 0), cA, voffA); PG8_STAGE(PG8_SA(0, 1), cA + hstep, voffA);
;     if (wr == 1) PG8_BAR;
;     PG8_WAIT_V(2); PG8_BAR;
;     PG8_STAGE(PG8_SB(1, 0), cB + kstep, voffB); PG8_STAGE(PG8_SA(1, 0), cA + kstep, voffA); PG8_STAGE(PG8_SB(1, 1), cB + hstep + kstep, voffB);
;     PG8_WAIT_V(6); PG8_BAR;
.LBB0_227:
	s_and_b32 s10, s5, 3
	s_lshl_b32 s31, s10, 5
	s_lshl_b32 s34, s10, 12
	s_mov_b64 s[10:11], 0x80
	s_add_i32 m0, s57, 0x18000
	v_lshl_add_u64 v[8:9], v[8:9], 0, s[10:11]
	s_lshl_b32 s30, s13, 13
	s_waitcnt vmcnt(2)
	s_barrier
	global_load_lds_dwordx4 v[8:9], off
	v_lshl_add_u64 v[6:7], v[6:7], 0, s[10:11]
	s_add_i32 m0, s57, 0x1a000
	s_add_i32 s61, s57, 0x8000
	s_add_i32 s62, s57, 0xa000
	global_load_lds_dwordx4 v[6:7], off
	v_lshl_add_u64 v[2:3], v[2:3], 0, s[10:11]
	s_mov_b32 m0, s61
	s_add_u32 s14, s52, 0x40080
	global_load_lds_dwordx4 v[2:3], off
	v_lshl_add_u64 v[2:3], v[4:5], 0, s[10:11]
	s_mov_b32 m0, s62
	s_addc_u32 s15, s53, 0
	global_load_lds_dwordx4 v[2:3], off
	s_add_i32 m0, s57, 0x1c000
	v_lshl_add_u64 v[2:3], s[14:15], 0, v[142:143]
	global_load_lds_dwordx4 v[2:3], off
	v_lshl_add_u64 v[2:3], s[14:15], 0, v[136:137]
	s_add_i32 m0, s57, 0x1e000
	v_bfe_u32 v4, v12, 4, 2
	global_load_lds_dwordx4 v[2:3], off
	v_and_b32_e32 v3, 15, v12
	v_lshlrev_b32_e32 v5, 4, v4
	v_lshl_or_b32 v1, s13, 6, v3
	v_lshl_or_b32 v3, v3, 6, v5
	v_lshlrev_b32_e32 v5, 2, v12
	v_and_b32_e32 v5, 32, v5
	s_cmpk_lt_u32 s12, 0x100
	s_sext_i32_i16 s15, s4
	v_bitop3_b32 v8, v3, s30, v5 bitop3:0xde
	v_bitop3_b32 v131, v3, s34, v5 bitop3:0xde
	s_cselect_b64 s[12:13], -1, 0
	s_lshl_b32 s4, s5, 4
	v_lshlrev_b32_e32 v3, 2, v4
	v_lshlrev_b32_e32 v2, 3, v4
	v_and_or_b32 v4, s4, 16, v3
	v_lshlrev_b32_e32 v3, 14, v15
	v_and_b32_e32 v3, 0xffff8000, v3
	v_lshl_add_u32 v3, v14, 11, v3
	v_and_b32_e32 v5, 1, v15
	v_lshl_or_b32 v3, v5, 6, v3
	v_lshl_add_u32 v152, v16, 1, v3
	v_lshlrev_b32_e32 v3, 14, v10
	v_lshlrev_b32_e32 v146, 2, v4
	v_and_b32_e32 v3, 0xffff8000, v3
	s_waitcnt vmcnt(6)
	v_lshl_add_u64 v[6:7], s[24:25], 0, v[146:147]
	s_mov_b64 s[4:5], 0xb80000
	v_lshl_add_u32 v3, v11, 11, v3
	v_and_b32_e32 v5, 1, v10
	s_and_b32 s30, s31, 64
	v_lshl_add_u64 v[148:149], v[6:7], 0, s[4:5]
	s_mov_b64 s[4:5], 0xbc0000
	v_lshl_or_b32 v3, v5, 6, v3
	s_add_i32 s63, 0, 0x10000
	s_add_i32 s64, 0, 0x14000
	v_lshl_add_u64 v[150:151], v[6:7], 0, s[4:5]
	v_mov_b32_e32 v153, v147
	v_lshl_add_u32 v154, v13, 1, v3
	v_mov_b32_e32 v155, v147
	v_mov_b64_e32 v[156:157], 0x880
	v_mov_b64_e32 v[158:159], 0x87f
	v_add_u32_e32 v168, s63, v131
	v_add_u32_e32 v169, s64, v131
	v_add_u32_e32 v170, 0, v8
	s_movk_i32 s65, 0x2200
	s_lshl_b32 s14, s31, 1
	v_lshlrev_b32_e32 v146, 1, v2
	s_lshl_b32 s30, s30, 1
	v_lshlrev_b32_e32 v160, 1, v4
	s_mov_b32 s66, 0
	s_barrier
	s_mov_b32 s98, 0
	s_branch .LBB0_230

.LBB0_233:
	ds_read_b128 v[172:175], v168
	ds_read_b128 v[176:179], v168 offset:1024
	ds_read_b128 v[180:183], v168 offset:2048
	ds_read_b128 v[184:187], v168 offset:3072
	ds_read_b128 v[188:191], v169
	ds_read_b128 v[192:195], v169 offset:1024
	ds_read_b128 v[196:199], v169 offset:2048
	ds_read_b128 v[200:203], v169 offset:3072
	s_add_u32 s52, s50, 0xfffc0080
	s_addc_u32 s53, s51, -1
	s_cmp_eq_u32 s70, 12
	s_cselect_b32 s55, s31, s53
	s_cselect_b32 s54, s37, s52
	s_cselect_b32 s53, s35, s69
	s_cselect_b32 s52, s67, s68
	v_lshl_add_u64 v[162:163], s[50:51], 0, v[152:153]
	s_add_i32 m0, s57, 0xc000
	ds_read_b128 v[204:207], v170
	ds_read_b128 v[208:211], v170 offset:1024
	ds_read_b128 v[216:219], v170 offset:2048
	ds_read_b128 v[220:223], v170 offset:3072
	ds_read_b128 v[224:227], v170 offset:4096
	ds_read_b128 v[228:231], v170 offset:5120
	ds_read_b128 v[232:235], v170 offset:6144
	ds_read_b128 v[236:239], v170 offset:7168
	global_load_lds_dwordx4 v[162:163], off
	v_lshl_add_u64 v[162:163], s[50:51], 0, v[154:155]
	s_add_i32 m0, s57, 0xe000
	s_nop 0
	global_load_lds_dwordx4 v[162:163], off
	s_cmp_lg_u32 s70, -2
	s_cbranch_scc1 .Lp1w_0_8
	s_cmp_lg_u32 s98, 1
	s_cbranch_scc1 .Lp1w_0_8
	s_waitcnt vmcnt(24)
	s_branch .Lp1w_0_d
.Lp1w_0_8:
	s_waitcnt vmcnt(8)
.Lp1w_0_d:
	s_waitcnt lgkmcnt(0)
	s_barrier
	s_setprio 1
	s_waitcnt lgkmcnt(0)
	v_mfma_f32_16x16x32_bf16 v[126:129], v[172:175], v[204:207], v[126:129]
	v_mfma_f32_16x16x32_bf16 v[122:125], v[180:183], v[204:207], v[122:125]
	v_mfma_f32_16x16x32_bf16 v[110:113], v[172:175], v[216:219], v[110:113]
	v_mfma_f32_16x16x32_bf16 v[106:109], v[180:183], v[216:219], v[106:109]
	v_mfma_f32_16x16x32_bf16 v[94:97], v[172:175], v[224:227], v[94:97]
	v_mfma_f32_16x16x32_bf16 v[90:93], v[180:183], v[224:227], v[90:93]
	v_mfma_f32_16x16x32_bf16 v[78:81], v[172:175], v[232:235], v[78:81]
	v_mfma_f32_16x16x32_bf16 v[74:77], v[180:183], v[232:235], v[74:77]
	v_mfma_f32_16x16x32_bf16 v[126:129], v[176:179], v[208:211], v[126:129]
	v_mfma_f32_16x16x32_bf16 v[122:125], v[184:187], v[208:211], v[122:125]
	v_mfma_f32_16x16x32_bf16 v[110:113], v[176:179], v[220:223], v[110:113]
	v_mfma_f32_16x16x32_bf16 v[106:109], v[184:187], v[220:223], v[106:109]
	v_mfma_f32_16x16x32_bf16 v[94:97], v[176:179], v[228:231], v[94:97]
	v_mfma_f32_16x16x32_bf16 v[90:93], v[184:187], v[228:231], v[90:93]
	v_mfma_f32_16x16x32_bf16 v[78:81], v[176:179], v[236:239], v[78:81]
	v_mfma_f32_16x16x32_bf16 v[74:77], v[184:187], v[236:239], v[74:77]
	s_setprio 0
	s_setprio 1
	v_mfma_f32_16x16x32_bf16 v[118:121], v[188:191], v[204:207], v[118:121]
	v_mfma_f32_16x16x32_bf16 v[114:117], v[196:199], v[204:207], v[114:117]
	v_mfma_f32_16x16x32_bf16 v[102:105], v[188:191], v[216:219], v[102:105]
	v_mfma_f32_16x16x32_bf16 v[98:101], v[196:199], v[216:219], v[98:101]
	v_mfma_f32_16x16x32_bf16 v[86:89], v[188:191], v[224:227], v[86:89]
	v_mfma_f32_16x16x32_bf16 v[82:85], v[196:199], v[224:227], v[82:85]
	v_mfma_f32_16x16x32_bf16 v[70:73], v[188:191], v[232:235], v[70:73]
	v_mfma_f32_16x16x32_bf16 v[66:69], v[196:199], v[232:235], v[66:69]
	v_mfma_f32_16x16x32_bf16 v[118:121], v[192:195], v[208:211], v[118:121]
	v_mfma_f32_16x16x32_bf16 v[114:117], v[200:203], v[208:211], v[114:117]
	v_mfma_f32_16x16x32_bf16 v[102:105], v[192:195], v[220:223], v[102:105]
	v_mfma_f32_16x16x32_bf16 v[98:101], v[200:203], v[220:223], v[98:101]
	v_mfma_f32_16x16x32_bf16 v[86:89], v[192:195], v[228:231], v[86:89]
	v_mfma_f32_16x16x32_bf16 v[82:85], v[200:203], v[228:231], v[82:85]
	v_mfma_f32_16x16x32_bf16 v[70:73], v[192:195], v[236:239], v[70:73]
	v_mfma_f32_16x16x32_bf16 v[66:69], v[200:203], v[236:239], v[66:69]
	s_setprio 0
	s_barrier
	s_add_i32 s71, s63, s21
	v_lshl_add_u64 v[162:163], s[52:53], 0, v[142:143]
	s_mov_b32 m0, s71
	ds_read_b128 v[204:207], v170 offset:16384
	ds_read_b128 v[208:211], v170 offset:17408
	ds_read_b128 v[216:219], v170 offset:18432
	ds_read_b128 v[220:223], v170 offset:19456
	ds_read_b128 v[224:227], v170 offset:20480
	ds_read_b128 v[228:231], v170 offset:21504
	ds_read_b128 v[232:235], v170 offset:22528
	ds_read_b128 v[236:239], v170 offset:23552
	global_load_lds_dwordx4 v[162:163], off
	s_add_i32 m0, s71, 0x2000
	s_add_u32 s72, s52, 0x40000
	v_lshl_add_u64 v[212:213], s[52:53], 0, v[136:137]
	s_addc_u32 s73, s53, 0
	s_add_i32 s71, s64, s21
	global_load_lds_dwordx4 v[212:213], off
	v_lshl_add_u64 v[240:241], s[72:73], 0, v[142:143]
	s_mov_b32 m0, s71
	v_lshl_add_u64 v[242:243], s[54:55], 0, v[138:139]
	global_load_lds_dwordx4 v[240:241], off
	v_lshl_add_u64 v[240:241], s[72:73], 0, v[136:137]
	s_add_i32 m0, s71, 0x2000
	s_nop 0
	global_load_lds_dwordx4 v[240:241], off
	v_lshl_add_u64 v[240:241], s[54:55], 0, v[144:145]
	s_mov_b32 m0, s57
	s_nop 0
	global_load_lds_dwordx4 v[240:241], off
	s_mov_b32 m0, s58
	s_nop 0
	global_load_lds_dwordx4 v[242:243], off
	s_cmp_lg_u32 s70, -2
	s_cbranch_scc1 .Lp1w_1_8
	s_cmp_lg_u32 s98, 1
	s_cbranch_scc1 .Lp1w_1_8
	s_waitcnt vmcnt(24)
	s_branch .Lp1w_1_d

.Lp1w_1_d:
	s_waitcnt lgkmcnt(0)
	s_barrier
	s_setprio 1
	s_waitcnt lgkmcnt(0)
	v_mfma_f32_16x16x32_bf16 v[62:65], v[172:175], v[204:207], v[62:65]
	v_mfma_f32_16x16x32_bf16 v[58:61], v[180:183], v[204:207], v[58:61]
	v_mfma_f32_16x16x32_bf16 v[46:49], v[172:175], v[216:219], v[46:49]
	v_mfma_f32_16x16x32_bf16 v[42:45], v[180:183], v[216:219], v[42:45]
	v_mfma_f32_16x16x32_bf16 v[30:33], v[172:175], v[224:227], v[30:33]
	v_mfma_f32_16x16x32_bf16 v[26:29], v[180:183], v[224:227], v[26:29]
	v_mfma_f32_16x16x32_bf16 v[14:17], v[172:175], v[232:235], v[14:17]
	v_mfma_f32_16x16x32_bf16 v[10:13], v[180:183], v[232:235], v[10:13]
	v_mfma_f32_16x16x32_bf16 v[62:65], v[176:179], v[208:211], v[62:65]
	v_mfma_f32_16x16x32_bf16 v[58:61], v[184:187], v[208:211], v[58:61]
	v_mfma_f32_16x16x32_bf16 v[46:49], v[176:179], v[220:223], v[46:49]
	v_mfma_f32_16x16x32_bf16 v[42:45], v[184:187], v[220:223], v[42:45]
	v_mfma_f32_16x16x32_bf16 v[30:33], v[176:179], v[228:231], v[30:33]
	v_mfma_f32_16x16x32_bf16 v[26:29], v[184:187], v[228:231], v[26:29]
	v_mfma_f32_16x16x32_bf16 v[14:17], v[176:179], v[236:239], v[14:17]
	v_mfma_f32_16x16x32_bf16 v[10:13], v[184:187], v[236:239], v[10:13]
	s_setprio 0
	s_setprio 1
	v_mfma_f32_16x16x32_bf16 v[54:57], v[188:191], v[204:207], v[54:57]
	v_mfma_f32_16x16x32_bf16 v[50:53], v[196:199], v[204:207], v[50:53]
	v_mfma_f32_16x16x32_bf16 v[38:41], v[188:191], v[216:219], v[38:41]
	v_mfma_f32_16x16x32_bf16 v[34:37], v[196:199], v[216:219], v[34:37]
	v_mfma_f32_16x16x32_bf16 v[22:25], v[188:191], v[224:227], v[22:25]
	v_mfma_f32_16x16x32_bf16 v[18:21], v[196:199], v[224:227], v[18:21]
	v_mfma_f32_16x16x32_bf16 v[6:9], v[188:191], v[232:235], v[6:9]
	v_mfma_f32_16x16x32_bf16 v[2:5], v[196:199], v[232:235], v[2:5]
	v_mfma_f32_16x16x32_bf16 v[54:57], v[192:195], v[208:211], v[54:57]
	v_mfma_f32_16x16x32_bf16 v[50:53], v[200:203], v[208:211], v[50:53]
	v_mfma_f32_16x16x32_bf16 v[38:41], v[192:195], v[220:223], v[38:41]
	v_mfma_f32_16x16x32_bf16 v[34:37], v[200:203], v[220:223], v[34:37]
	v_mfma_f32_16x16x32_bf16 v[22:25], v[192:195], v[228:231], v[22:25]
	v_mfma_f32_16x16x32_bf16 v[18:21], v[200:203], v[228:231], v[18:21]
	v_mfma_f32_16x16x32_bf16 v[6:9], v[192:195], v[236:239], v[6:9]
	v_mfma_f32_16x16x32_bf16 v[2:5], v[200:203], v[236:239], v[2:5]
	s_setprio 0
	s_barrier
	s_add_i32 s71, 0, 0x18000
	v_add_u32_e32 v161, s71, v131
	s_add_i32 s72, 0, 0x1c000
	ds_read_b128 v[172:175], v161
	ds_read_b128 v[176:179], v161 offset:1024
	ds_read_b128 v[180:183], v161 offset:2048
	ds_read_b128 v[184:187], v161 offset:3072
	v_add_u32_e32 v161, s72, v131
	ds_read_b128 v[188:191], v161
	ds_read_b128 v[192:195], v161 offset:1024
	ds_read_b128 v[196:199], v161 offset:2048
	ds_read_b128 v[200:203], v161 offset:3072
	s_add_u32 s54, s54, 0x40000
	s_addc_u32 s55, s55, 0
	s_mov_b32 m0, s59
	v_lshl_add_u64 v[244:245], s[54:55], 0, v[144:145]
	ds_read_b128 v[204:207], v170 offset:32768
	ds_read_b128 v[208:211], v170 offset:33792
	ds_read_b128 v[216:219], v170 offset:34816
	ds_read_b128 v[220:223], v170 offset:35840
	ds_read_b128 v[224:227], v170 offset:36864
	ds_read_b128 v[228:231], v170 offset:37888
	ds_read_b128 v[232:235], v170 offset:38912
	ds_read_b128 v[236:239], v170 offset:39936
	global_load_lds_dwordx4 v[244:245], off
	v_lshl_add_u64 v[244:245], s[54:55], 0, v[138:139]
	s_mov_b32 m0, s60
	s_nop 0
	global_load_lds_dwordx4 v[244:245], off
	s_waitcnt vmcnt(8)
	s_waitcnt lgkmcnt(0)
	s_barrier
	s_setprio 1
	s_waitcnt lgkmcnt(0)
	v_mfma_f32_16x16x32_bf16 v[126:129], v[172:175], v[204:207], v[126:129]
	v_mfma_f32_16x16x32_bf16 v[122:125], v[180:183], v[204:207], v[122:125]
	v_mfma_f32_16x16x32_bf16 v[110:113], v[172:175], v[216:219], v[110:113]
	v_mfma_f32_16x16x32_bf16 v[106:109], v[180:183], v[216:219], v[106:109]
	v_mfma_f32_16x16x32_bf16 v[94:97], v[172:175], v[224:227], v[94:97]
	v_mfma_f32_16x16x32_bf16 v[90:93], v[180:183], v[224:227], v[90:93]
	v_mfma_f32_16x16x32_bf16 v[78:81], v[172:175], v[232:235], v[78:81]
	v_mfma_f32_16x16x32_bf16 v[74:77], v[180:183], v[232:235], v[74:77]
	v_mfma_f32_16x16x32_bf16 v[126:129], v[176:179], v[208:211], v[126:129]
	v_mfma_f32_16x16x32_bf16 v[122:125], v[184:187], v[208:211], v[122:125]
	v_mfma_f32_16x16x32_bf16 v[110:113], v[176:179], v[220:223], v[110:113]
	v_mfma_f32_16x16x32_bf16 v[106:109], v[184:187], v[220:223], v[106:109]
	v_mfma_f32_16x16x32_bf16 v[94:97], v[176:179], v[228:231], v[94:97]
	v_mfma_f32_16x16x32_bf16 v[90:93], v[184:187], v[228:231], v[90:93]
	v_mfma_f32_16x16x32_bf16 v[78:81], v[176:179], v[236:239], v[78:81]
	v_mfma_f32_16x16x32_bf16 v[74:77], v[184:187], v[236:239], v[74:77]
	s_setprio 0
	s_setprio 1
	v_mfma_f32_16x16x32_bf16 v[118:121], v[188:191], v[204:207], v[118:121]
	v_mfma_f32_16x16x32_bf16 v[114:117], v[196:199], v[204:207], v[114:117]
	v_mfma_f32_16x16x32_bf16 v[102:105], v[188:191], v[216:219], v[102:105]
	v_mfma_f32_16x16x32_bf16 v[98:101], v[196:199], v[216:219], v[98:101]
	v_mfma_f32_16x16x32_bf16 v[86:89], v[188:191], v[224:227], v[86:89]
	v_mfma_f32_16x16x32_bf16 v[82:85], v[196:199], v[224:227], v[82:85]
	v_mfma_f32_16x16x32_bf16 v[70:73], v[188:191], v[232:235], v[70:73]
	v_mfma_f32_16x16x32_bf16 v[66:69], v[196:199], v[232:235], v[66:69]
	v_mfma_f32_16x16x32_bf16 v[118:121], v[192:195], v[208:211], v[118:121]
	v_mfma_f32_16x16x32_bf16 v[114:117], v[200:203], v[208:211], v[114:117]
	v_mfma_f32_16x16x32_bf16 v[102:105], v[192:195], v[220:223], v[102:105]
	v_mfma_f32_16x16x32_bf16 v[98:101], v[200:203], v[220:223], v[98:101]
	v_mfma_f32_16x16x32_bf16 v[86:89], v[192:195], v[228:231], v[86:89]
	v_mfma_f32_16x16x32_bf16 v[82:85], v[200:203], v[228:231], v[82:85]
	v_mfma_f32_16x16x32_bf16 v[70:73], v[192:195], v[236:239], v[70:73]
	v_mfma_f32_16x16x32_bf16 v[66:69], v[200:203], v[236:239], v[66:69]
	s_setprio 0
	s_barrier
; #define PG8_BAR __builtin_amdgcn_s_barrier()
; template <class Epi, bool HOOK = false>
; DI void gemm_phase(LAS unsigned char* lds, const Gemm g, const StaticOrder& S, const Epi& E) {
;     ...
;         if constexpr (HOOK) {
;             for (int t = 0; t < (nt >> 1); t += 2) PG8_KBODY();
;             E.hook(acc, cur, wr, wc, fr, fq);
;             for (int t = (nt >> 1); t < nt; t += 2) PG8_KBODY();
;         } else {
;             for (int t = 0; t < nt; t += 2) PG8_KBODY();
;         }
;     ...
;         if (wr == 0) PG8_BAR;
	s_add_i32 s54, s71, s21
	v_lshl_add_u64 v[162:163], v[162:163], 0, s[10:11]
	s_mov_b32 m0, s54
	ds_read_b128 v[204:207], v170 offset:49152
	ds_read_b128 v[208:211], v170 offset:50176
	ds_read_b128 v[216:219], v170 offset:51200
	ds_read_b128 v[220:223], v170 offset:52224
	ds_read_b128 v[224:227], v170 offset:53248
	ds_read_b128 v[228:231], v170 offset:54272
	ds_read_b128 v[232:235], v170 offset:55296
	ds_read_b128 v[236:239], v170 offset:56320
	global_load_lds_dwordx4 v[162:163], off
	s_add_i32 m0, s54, 0x2000
	s_add_u32 s52, s52, 0x40080
	v_lshl_add_u64 v[162:163], v[212:213], 0, s[10:11]
	s_addc_u32 s53, s53, 0
	s_add_i32 s54, s72, s21
	global_load_lds_dwordx4 v[162:163], off
	v_lshl_add_u64 v[162:163], s[52:53], 0, v[142:143]
	s_mov_b32 m0, s54
	s_nop 0
	global_load_lds_dwordx4 v[162:163], off
	v_lshl_add_u64 v[162:163], s[52:53], 0, v[136:137]
	s_add_i32 m0, s54, 0x2000
	s_nop 0
	global_load_lds_dwordx4 v[162:163], off
	v_lshl_add_u64 v[162:163], v[240:241], 0, s[10:11]
	s_mov_b32 m0, s61
	s_nop 0
	global_load_lds_dwordx4 v[162:163], off
	v_lshl_add_u64 v[162:163], v[242:243], 0, s[10:11]
	s_mov_b32 m0, s62
	s_nop 0
	global_load_lds_dwordx4 v[162:163], off
	s_waitcnt vmcnt(8)
	s_waitcnt lgkmcnt(0)
	s_barrier
	s_setprio 1
	s_waitcnt lgkmcnt(0)
	v_mfma_f32_16x16x32_bf16 v[62:65], v[172:175], v[204:207], v[62:65]
	v_mfma_f32_16x16x32_bf16 v[58:61], v[180:183], v[204:207], v[58:61]
	v_mfma_f32_16x16x32_bf16 v[46:49], v[172:175], v[216:219], v[46:49]
	v_mfma_f32_16x16x32_bf16 v[42:45], v[180:183], v[216:219], v[42:45]
	v_mfma_f32_16x16x32_bf16 v[30:33], v[172:175], v[224:227], v[30:33]
	v_mfma_f32_16x16x32_bf16 v[26:29], v[180:183], v[224:227], v[26:29]
	v_mfma_f32_16x16x32_bf16 v[14:17], v[172:175], v[232:235], v[14:17]
	v_mfma_f32_16x16x32_bf16 v[10:13], v[180:183], v[232:235], v[10:13]
	v_mfma_f32_16x16x32_bf16 v[62:65], v[176:179], v[208:211], v[62:65]
	v_mfma_f32_16x16x32_bf16 v[58:61], v[184:187], v[208:211], v[58:61]
	v_mfma_f32_16x16x32_bf16 v[46:49], v[176:179], v[220:223], v[46:49]
	v_mfma_f32_16x16x32_bf16 v[42:45], v[184:187], v[220:223], v[42:45]
	v_mfma_f32_16x16x32_bf16 v[30:33], v[176:179], v[228:231], v[30:33]
	v_mfma_f32_16x16x32_bf16 v[26:29], v[184:187], v[228:231], v[26:29]
	v_mfma_f32_16x16x32_bf16 v[14:17], v[176:179], v[236:239], v[14:17]
	v_mfma_f32_16x16x32_bf16 v[10:13], v[184:187], v[236:239], v[10:13]
	s_setprio 0
	s_setprio 1
	v_mfma_f32_16x16x32_bf16 v[54:57], v[188:191], v[204:207], v[54:57]
	v_mfma_f32_16x16x32_bf16 v[50:53], v[196:199], v[204:207], v[50:53]
	v_mfma_f32_16x16x32_bf16 v[38:41], v[188:191], v[216:219], v[38:41]
	v_mfma_f32_16x16x32_bf16 v[34:37], v[196:199], v[216:219], v[34:37]
	v_mfma_f32_16x16x32_bf16 v[22:25], v[188:191], v[224:227], v[22:25]
	v_mfma_f32_16x16x32_bf16 v[18:21], v[196:199], v[224:227], v[18:21]
	v_mfma_f32_16x16x32_bf16 v[6:9], v[188:191], v[232:235], v[6:9]
	v_mfma_f32_16x16x32_bf16 v[2:5], v[196:199], v[232:235], v[2:5]
	v_mfma_f32_16x16x32_bf16 v[54:57], v[192:195], v[208:211], v[54:57]
	v_mfma_f32_16x16x32_bf16 v[50:53], v[200:203], v[208:211], v[50:53]
	v_mfma_f32_16x16x32_bf16 v[38:41], v[192:195], v[220:223], v[38:41]
	v_mfma_f32_16x16x32_bf16 v[34:37], v[200:203], v[220:223], v[34:37]
	v_mfma_f32_16x16x32_bf16 v[22:25], v[192:195], v[228:231], v[22:25]
	v_mfma_f32_16x16x32_bf16 v[18:21], v[200:203], v[228:231], v[18:21]
	v_mfma_f32_16x16x32_bf16 v[6:9], v[192:195], v[236:239], v[6:9]
	v_mfma_f32_16x16x32_bf16 v[2:5], v[200:203], v[236:239], v[2:5]
	s_setprio 0
	s_barrier
	s_add_i32 s70, s70, 2
	s_add_u32 s50, s50, 0x100
	s_addc_u32 s51, s51, 0
	s_add_u32 s68, s68, 0x100
	s_addc_u32 s69, s69, 0
	s_cmp_gt_u32 s70, 13
	s_cbranch_scc0 .LBB0_233
	s_and_b64 vcc, exec, s[12:13]
	s_cbranch_vccz .LBB0_236
	s_barrier
; DI unsigned pk2(float lo, float hi) { const f32x2 v = {lo, hi}; const bf16x2_t b = __builtin_convertvector(v, bf16x2_t); return __builtin_bit_cast(unsigned, b); }
;     DI void operator()(const Acc& acc, const Unit& u, int wr, int wc, int fr, int fq) const {
;     ...
;         } else {
; #pragma unroll
;             for (int ai = 0; ai < 2; ++ai)
; #pragma unroll
;                 for (int m = 0; m < 4; ++m) {
;                     const int r = row0 + ai * 128 + m * 16;
; #pragma unroll
;                     for (int bj = 0; bj < 2; ++bj) {
;                         const f32x4 v0 = acc[ai][bj][m][0], v1 = acc[ai][bj][m][1];
;                         u32x4 w; w.x = pk2(v0[0], v0[1]); w.y = pk2(v0[2], v0[3]); w.z = pk2(v1[0], v1[1]); w.w = pk2(v1[2], v1[3]);
;                         *(u32x4*)(Z + (size_t)r * NZ + u.pn * 256 + bj * 128 + wc * 32 + 8 * fq) = w;
;                     }
;                 }
;         }
.LBB0_236:
	v_lshl_add_u32 v178, s6, 8, v1
	s_lshl_b32 s6, s15, 8
	s_cmp_lt_i32 s15, 7
	s_mov_b64 s[50:51], -1
	v_or_b32_e32 v177, 16, v178
	v_or_b32_e32 v176, 32, v178
	v_or_b32_e32 v175, 48, v178
	v_add_u32_e32 v174, 0x80, v178
	v_add_u32_e32 v173, 0x90, v178
	v_add_u32_e32 v172, 0xa0, v178
	v_add_u32_e32 v171, 0xb0, v178
	s_cbranch_scc1 .LBB0_239
	v_mov_b64_e32 v[162:163], s[22:23]
	v_mad_i64_i32 v[184:185], s[50:51], v178, s65, v[162:163]
	s_lshl_b64 s[50:51], s[6:7], 1
	s_nop 0
	v_lshl_add_u64 v[184:185], v[184:185], 0, s[50:51]
	s_mov_b32 s15, s7
	v_lshl_add_u64 v[184:185], v[184:185], 0, s[14:15]
	v_cvt_pk_bf16_f32 v180, v126, v127
	v_cvt_pk_bf16_f32 v181, v128, v129
	v_cvt_pk_bf16_f32 v182, v122, v123
	v_cvt_pk_bf16_f32 v183, v124, v125
	v_lshl_add_u64 v[184:185], v[184:185], 0, v[146:147]
	global_store_dwordx4 v[184:185], v[180:183], off
	s_nop 1
	v_cvt_pk_bf16_f32 v180, v118, v119
	v_cvt_pk_bf16_f32 v181, v120, v121
	v_cvt_pk_bf16_f32 v182, v114, v115
	v_cvt_pk_bf16_f32 v183, v116, v117
	global_store_dwordx4 v[184:185], v[180:183], off offset:256
	v_mad_i64_i32 v[184:185], s[52:53], v177, s65, v[162:163]
	v_lshl_add_u64 v[184:185], v[184:185], 0, s[50:51]
	v_lshl_add_u64 v[184:185], v[184:185], 0, s[14:15]
	v_cvt_pk_bf16_f32 v180, v110, v111
	v_cvt_pk_bf16_f32 v181, v112, v113
	v_cvt_pk_bf16_f32 v182, v106, v107
	v_cvt_pk_bf16_f32 v183, v108, v109
	v_lshl_add_u64 v[184:185], v[184:185], 0, v[146:147]
	global_store_dwordx4 v[184:185], v[180:183], off
	s_nop 1
	v_cvt_pk_bf16_f32 v180, v102, v103
	v_cvt_pk_bf16_f32 v181, v104, v105
	v_cvt_pk_bf16_f32 v182, v98, v99
	v_cvt_pk_bf16_f32 v183, v100, v101
	global_store_dwordx4 v[184:185], v[180:183], off offset:256
	v_mad_i64_i32 v[184:185], s[52:53], v176, s65, v[162:163]
	v_lshl_add_u64 v[184:185], v[184:185], 0, s[50:51]
	v_lshl_add_u64 v[184:185], v[184:185], 0, s[14:15]
	v_cvt_pk_bf16_f32 v180, v94, v95
	v_cvt_pk_bf16_f32 v181, v96, v97
	v_cvt_pk_bf16_f32 v182, v90, v91
	v_cvt_pk_bf16_f32 v183, v92, v93
	v_lshl_add_u64 v[184:185], v[184:185], 0, v[146:147]
	global_store_dwordx4 v[184:185], v[180:183], off
	s_nop 1
	v_cvt_pk_bf16_f32 v180, v86, v87
	v_cvt_pk_bf16_f32 v181, v88, v89
	v_cvt_pk_bf16_f32 v182, v82, v83
	v_cvt_pk_bf16_f32 v183, v84, v85
	global_store_dwordx4 v[184:185], v[180:183], off offset:256
	v_mad_i64_i32 v[184:185], s[52:53], v175, s65, v[162:163]
	v_lshl_add_u64 v[184:185], v[184:185], 0, s[50:51]
	v_lshl_add_u64 v[184:185], v[184:185], 0, s[14:15]
	v_cvt_pk_bf16_f32 v180, v78, v79
	v_cvt_pk_bf16_f32 v181, v80, v81
	v_cvt_pk_bf16_f32 v182, v74, v75
	v_cvt_pk_bf16_f32 v183, v76, v77
	v_lshl_add_u64 v[184:185], v[184:185], 0, v[146:147]
	global_store_dwordx4 v[184:185], v[180:183], off
	s_nop 1
	v_cvt_pk_bf16_f32 v180, v70, v71
	v_cvt_pk_bf16_f32 v181, v72, v73
	v_cvt_pk_bf16_f32 v182, v66, v67
	v_cvt_pk_bf16_f32 v183, v68, v69
	global_store_dwordx4 v[184:185], v[180:183], off offset:256
	v_mad_i64_i32 v[184:185], s[52:53], v174, s65, v[162:163]
	v_lshl_add_u64 v[184:185], v[184:185], 0, s[50:51]
	v_lshl_add_u64 v[184:185], v[184:185], 0, s[14:15]
	v_cvt_pk_bf16_f32 v180, v62, v63
	v_cvt_pk_bf16_f32 v181, v64, v65
	v_cvt_pk_bf16_f32 v182, v58, v59
	v_cvt_pk_bf16_f32 v183, v60, v61
	v_lshl_add_u64 v[184:185], v[184:185], 0, v[146:147]
	global_store_dwordx4 v[184:185], v[180:183], off
	s_nop 1
	v_cvt_pk_bf16_f32 v180, v54, v55
	v_cvt_pk_bf16_f32 v181, v56, v57
	v_cvt_pk_bf16_f32 v182, v50, v51
	v_cvt_pk_bf16_f32 v183, v52, v53
	global_store_dwordx4 v[184:185], v[180:183], off offset:256
	v_mad_i64_i32 v[184:185], s[52:53], v173, s65, v[162:163]
	v_lshl_add_u64 v[184:185], v[184:185], 0, s[50:51]
	v_lshl_add_u64 v[184:185], v[184:185], 0, s[14:15]
	v_cvt_pk_bf16_f32 v180, v46, v47
	v_cvt_pk_bf16_f32 v181, v48, v49
	v_cvt_pk_bf16_f32 v182, v42, v43
	v_cvt_pk_bf16_f32 v183, v44, v45
	v_lshl_add_u64 v[184:185], v[184:185], 0, v[146:147]
	global_store_dwordx4 v[184:185], v[180:183], off
	s_nop 1
	v_cvt_pk_bf16_f32 v180, v38, v39
	v_cvt_pk_bf16_f32 v181, v40, v41
	v_cvt_pk_bf16_f32 v182, v34, v35
	v_cvt_pk_bf16_f32 v183, v36, v37
	global_store_dwordx4 v[184:185], v[180:183], off offset:256
	v_mad_i64_i32 v[184:185], s[52:53], v172, s65, v[162:163]
	v_lshl_add_u64 v[184:185], v[184:185], 0, s[50:51]
	v_lshl_add_u64 v[184:185], v[184:185], 0, s[14:15]
	v_mad_i64_i32 v[162:163], s[52:53], v171, s65, v[162:163]
	v_cvt_pk_bf16_f32 v180, v30, v31
	v_cvt_pk_bf16_f32 v181, v32, v33
	v_cvt_pk_bf16_f32 v182, v26, v27
	v_cvt_pk_bf16_f32 v183, v28, v29
	v_lshl_add_u64 v[184:185], v[184:185], 0, v[146:147]
	v_lshl_add_u64 v[162:163], v[162:163], 0, s[50:51]
	global_store_dwordx4 v[184:185], v[180:183], off
	v_lshl_add_u64 v[162:163], v[162:163], 0, s[14:15]
	v_lshl_add_u64 v[162:163], v[162:163], 0, v[146:147]
	v_cvt_pk_bf16_f32 v180, v22, v23
	v_cvt_pk_bf16_f32 v181, v24, v25
	v_cvt_pk_bf16_f32 v182, v18, v19
	v_cvt_pk_bf16_f32 v183, v20, v21
	global_store_dwordx4 v[184:185], v[180:183], off offset:256
	s_nop 1
	v_cvt_pk_bf16_f32 v180, v14, v15
	v_cvt_pk_bf16_f32 v181, v16, v17
	v_cvt_pk_bf16_f32 v182, v10, v11
	v_cvt_pk_bf16_f32 v183, v12, v13
	global_store_dwordx4 v[162:163], v[180:183], off
	s_nop 1
	v_cvt_pk_bf16_f32 v180, v6, v7
	v_cvt_pk_bf16_f32 v181, v8, v9
	v_cvt_pk_bf16_f32 v182, v2, v3
	v_cvt_pk_bf16_f32 v183, v4, v5
	global_store_dwordx4 v[162:163], v[180:183], off offset:256
	s_mov_b32 s98, 1
	s_cbranch_execz .LBB0_240

; DI unsigned pk2(float lo, float hi) { const f32x2 v = {lo, hi}; const bf16x2_t b = __builtin_convertvector(v, bf16x2_t); return __builtin_bit_cast(unsigned, b); }
;     DI void operator()(const Acc& acc, const Unit& u, int wr, int wc, int fr, int fq) const {
;         const int row0 = u.pm * 256 + wr * 64 + fr;
;         if (u.pn < 7) {
;             const int jj = 16 * (wc & 1) + 4 * fq;
; #pragma unroll
;             for (int ai = 0; ai < 2; ++ai)
; #pragma unroll
;                 for (int m = 0; m < 4; ++m) {
;                     const int r = row0 + ai * 128 + m * 16; const int pos = r & (SEQ - 1);
;                     const f32x4 c = *(const f32x4*)(ropec + pos * 32 + jj), s = *(const f32x4*)(ropes + pos * 32 + jj);
; #pragma unroll
;                     for (int bj = 0; bj < 2; ++bj) {
;                         const f32x4 x1 = acc[ai][bj][m][0], x2 = acc[ai][bj][m][1];
;                         const f32x4 o1 = x1 * c - x2 * s, o2 = x1 * s + x2 * c;
;                         bf16_t* p = Z + (size_t)r * NZ + u.pn * 256 + bj * 128 + (wc >> 1) * 64 + jj;
;                         u32x2 w1; w1.x = pk2(o1[0], o1[1]); w1.y = pk2(o1[2], o1[3]);
;                         u32x2 w2; w2.x = pk2(o2[0], o2[1]); w2.y = pk2(o2[2], o2[3]);
;                         *(u32x2*)p = w1; *(u32x2*)(p + 32) = w2;
;                     }
;                 }
.LBB0_240:
	s_mov_b32 s98, 0
	v_lshlrev_b32_e32 v161, 7, v178
	v_and_b32_e32 v162, 0x3e780, v161
	v_mov_b32_e32 v163, v147
	v_lshl_add_u64 v[180:181], v[150:151], 0, v[162:163]
	global_load_dwordx4 v[180:183], v[180:181], off
	v_lshl_add_u64 v[162:163], v[148:149], 0, v[162:163]
	global_load_dwordx4 v[184:187], v[162:163], off
	s_ashr_i32 s51, s6, 31
	s_mov_b32 s50, s6
	v_mov_b64_e32 v[162:163], s[22:23]
	v_mad_i64_i32 v[188:189], s[52:53], v178, s65, v[162:163]
	s_lshl_b64 s[50:51], s[50:51], 1
	s_mov_b32 s31, s7
	v_lshl_add_u64 v[188:189], v[188:189], 0, s[50:51]
	v_mov_b32_e32 v161, v147
	v_lshlrev_b32_e32 v190, 7, v177
	v_lshl_add_u64 v[188:189], v[188:189], 0, s[30:31]
	v_mov_b32_e32 v179, v147
	v_and_b32_e32 v178, 0x3ef80, v190
	v_lshl_add_u64 v[188:189], v[188:189], 0, v[160:161]
	v_lshl_add_u64 v[190:191], v[150:151], 0, v[178:179]
	s_waitcnt vmcnt(0)
	v_pk_mul_f32 v[192:193], v[124:125], v[182:183]
	v_pk_mul_f32 v[194:195], v[122:123], v[180:181]
	v_pk_mul_f32 v[196:197], v[128:129], v[182:183]
	v_pk_mul_f32 v[198:199], v[126:127], v[180:181]
	v_pk_mul_f32 v[200:201], v[116:117], v[182:183]
	v_pk_mul_f32 v[202:203], v[114:115], v[180:181]
	v_pk_mul_f32 v[182:183], v[120:121], v[182:183]
	v_pk_mul_f32 v[180:181], v[118:119], v[180:181]
	v_pk_fma_f32 v[128:129], v[128:129], v[186:187], v[192:193] neg_lo:[0,0,1] neg_hi:[0,0,1]
	v_pk_fma_f32 v[126:127], v[126:127], v[184:185], v[194:195] neg_lo:[0,0,1] neg_hi:[0,0,1]
	v_pk_fma_f32 v[124:125], v[124:125], v[186:187], v[196:197]
	v_pk_fma_f32 v[122:123], v[122:123], v[184:185], v[198:199]
	v_pk_fma_f32 v[120:121], v[120:121], v[186:187], v[200:201] neg_lo:[0,0,1] neg_hi:[0,0,1]
	v_pk_fma_f32 v[118:119], v[118:119], v[184:185], v[202:203] neg_lo:[0,0,1] neg_hi:[0,0,1]
	v_pk_fma_f32 v[116:117], v[116:117], v[186:187], v[182:183]
	v_pk_fma_f32 v[114:115], v[114:115], v[184:185], v[180:181]
	v_cvt_pk_bf16_f32 v126, v126, v127
	v_cvt_pk_bf16_f32 v127, v128, v129
	v_cvt_pk_bf16_f32 v122, v122, v123
	v_cvt_pk_bf16_f32 v123, v124, v125
	v_cvt_pk_bf16_f32 v118, v118, v119
	v_cvt_pk_bf16_f32 v119, v120, v121
	v_cvt_pk_bf16_f32 v114, v114, v115
	v_cvt_pk_bf16_f32 v115, v116, v117
	global_store_dwordx2 v[188:189], v[126:127], off
	global_store_dwordx2 v[188:189], v[122:123], off offset:64
	global_store_dwordx2 v[188:189], v[118:119], off offset:256
	global_store_dwordx2 v[188:189], v[114:115], off offset:320
	global_load_dwordx4 v[114:117], v[190:191], off
	v_lshl_add_u64 v[118:119], v[148:149], 0, v[178:179]
	global_load_dwordx4 v[118:121], v[118:119], off
	v_mad_i64_i32 v[124:125], s[52:53], v177, s65, v[162:163]
	v_lshl_add_u64 v[124:125], v[124:125], 0, s[50:51]
	v_lshlrev_b32_e32 v122, 7, v176
	v_lshl_add_u64 v[124:125], v[124:125], 0, s[30:31]
	v_mov_b32_e32 v123, v147
	v_and_b32_e32 v122, 0x3f780, v122
	v_lshl_add_u64 v[124:125], v[124:125], 0, v[160:161]
	v_lshl_add_u64 v[126:127], v[150:151], 0, v[122:123]
	s_waitcnt vmcnt(1)
	v_pk_mul_f32 v[128:129], v[108:109], v[116:117]
	v_pk_mul_f32 v[178:179], v[106:107], v[114:115]
	v_pk_mul_f32 v[180:181], v[112:113], v[116:117]
	v_pk_mul_f32 v[182:183], v[110:111], v[114:115]
	v_pk_mul_f32 v[184:185], v[100:101], v[116:117]
	v_pk_mul_f32 v[186:187], v[98:99], v[114:115]
	v_pk_mul_f32 v[116:117], v[104:105], v[116:117]
	v_pk_mul_f32 v[114:115], v[102:103], v[114:115]
	s_waitcnt vmcnt(0)
	v_pk_fma_f32 v[112:113], v[112:113], v[120:121], v[128:129] neg_lo:[0,0,1] neg_hi:[0,0,1]
	v_pk_fma_f32 v[110:111], v[110:111], v[118:119], v[178:179] neg_lo:[0,0,1] neg_hi:[0,0,1]
	v_pk_fma_f32 v[108:109], v[108:109], v[120:121], v[180:181]
	v_pk_fma_f32 v[106:107], v[106:107], v[118:119], v[182:183]
	v_pk_fma_f32 v[104:105], v[104:105], v[120:121], v[184:185] neg_lo:[0,0,1] neg_hi:[0,0,1]
	v_pk_fma_f32 v[102:103], v[102:103], v[118:119], v[186:187] neg_lo:[0,0,1] neg_hi:[0,0,1]
	v_pk_fma_f32 v[100:101], v[100:101], v[120:121], v[116:117]
	v_pk_fma_f32 v[98:99], v[98:99], v[118:119], v[114:115]
	v_cvt_pk_bf16_f32 v110, v110, v111
	v_cvt_pk_bf16_f32 v111, v112, v113
	v_cvt_pk_bf16_f32 v106, v106, v107
	v_cvt_pk_bf16_f32 v107, v108, v109
	v_cvt_pk_bf16_f32 v102, v102, v103
	v_cvt_pk_bf16_f32 v103, v104, v105
	v_cvt_pk_bf16_f32 v98, v98, v99
	v_cvt_pk_bf16_f32 v99, v100, v101
	global_store_dwordx2 v[124:125], v[110:111], off
	global_store_dwordx2 v[124:125], v[106:107], off offset:64
	global_store_dwordx2 v[124:125], v[102:103], off offset:256
	global_store_dwordx2 v[124:125], v[98:99], off offset:320
	global_load_dwordx4 v[98:101], v[126:127], off
	v_lshl_add_u64 v[102:103], v[148:149], 0, v[122:123]
	global_load_dwordx4 v[102:105], v[102:103], off
	v_mad_i64_i32 v[108:109], s[52:53], v176, s65, v[162:163]
	v_lshl_add_u64 v[108:109], v[108:109], 0, s[50:51]
	v_lshlrev_b32_e32 v106, 7, v175
	v_lshl_add_u64 v[108:109], v[108:109], 0, s[30:31]
	v_mov_b32_e32 v107, v147
	v_and_b32_e32 v106, 0x3ff80, v106
	v_lshl_add_u64 v[108:109], v[108:109], 0, v[160:161]
	v_lshl_add_u64 v[110:111], v[150:151], 0, v[106:107]
	s_waitcnt vmcnt(1)
	v_pk_mul_f32 v[112:113], v[92:93], v[100:101]
	v_pk_mul_f32 v[114:115], v[90:91], v[98:99]
	v_pk_mul_f32 v[116:117], v[96:97], v[100:101]
	v_pk_mul_f32 v[118:119], v[94:95], v[98:99]
	v_pk_mul_f32 v[120:121], v[84:85], v[100:101]
	v_pk_mul_f32 v[122:123], v[82:83], v[98:99]
	v_pk_mul_f32 v[100:101], v[88:89], v[100:101]
	v_pk_mul_f32 v[98:99], v[86:87], v[98:99]
	s_waitcnt vmcnt(0)
; DI unsigned pk2(float lo, float hi) { const f32x2 v = {lo, hi}; const bf16x2_t b = __builtin_convertvector(v, bf16x2_t); return __builtin_bit_cast(unsigned, b); }
;     DI void operator()(const Acc& acc, const Unit& u, int wr, int wc, int fr, int fq) const {
;         const int row0 = u.pm * 256 + wr * 64 + fr;
;         if (u.pn < 7) {
;             const int jj = 16 * (wc & 1) + 4 * fq;
; #pragma unroll
;             for (int ai = 0; ai < 2; ++ai)
; #pragma unroll
;                 for (int m = 0; m < 4; ++m) {
;                     const int r = row0 + ai * 128 + m * 16; const int pos = r & (SEQ - 1);
;                     const f32x4 c = *(const f32x4*)(ropec + pos * 32 + jj), s = *(const f32x4*)(ropes + pos * 32 + jj);
; #pragma unroll
;                     for (int bj = 0; bj < 2; ++bj) {
;                         const f32x4 x1 = acc[ai][bj][m][0], x2 = acc[ai][bj][m][1];
;                         const f32x4 o1 = x1 * c - x2 * s, o2 = x1 * s + x2 * c;
;                         bf16_t* p = Z + (size_t)r * NZ + u.pn * 256 + bj * 128 + (wc >> 1) * 64 + jj;
;                         u32x2 w1; w1.x = pk2(o1[0], o1[1]); w1.y = pk2(o1[2], o1[3]);
;                         u32x2 w2; w2.x = pk2(o2[0], o2[1]); w2.y = pk2(o2[2], o2[3]);
;                         *(u32x2*)p = w1; *(u32x2*)(p + 32) = w2;
;                     }
;                 }
	v_pk_fma_f32 v[96:97], v[96:97], v[104:105], v[112:113] neg_lo:[0,0,1] neg_hi:[0,0,1]
	v_pk_fma_f32 v[94:95], v[94:95], v[102:103], v[114:115] neg_lo:[0,0,1] neg_hi:[0,0,1]
	v_pk_fma_f32 v[92:93], v[92:93], v[104:105], v[116:117]
	v_pk_fma_f32 v[90:91], v[90:91], v[102:103], v[118:119]
	v_pk_fma_f32 v[88:89], v[88:89], v[104:105], v[120:121] neg_lo:[0,0,1] neg_hi:[0,0,1]
	v_pk_fma_f32 v[86:87], v[86:87], v[102:103], v[122:123] neg_lo:[0,0,1] neg_hi:[0,0,1]
	v_pk_fma_f32 v[84:85], v[84:85], v[104:105], v[100:101]
	v_pk_fma_f32 v[82:83], v[82:83], v[102:103], v[98:99]
	v_cvt_pk_bf16_f32 v94, v94, v95
	v_cvt_pk_bf16_f32 v95, v96, v97
	v_cvt_pk_bf16_f32 v90, v90, v91
	v_cvt_pk_bf16_f32 v91, v92, v93
	v_cvt_pk_bf16_f32 v86, v86, v87
	v_cvt_pk_bf16_f32 v87, v88, v89
	v_cvt_pk_bf16_f32 v82, v82, v83
	v_cvt_pk_bf16_f32 v83, v84, v85
	global_store_dwordx2 v[108:109], v[94:95], off
	global_store_dwordx2 v[108:109], v[90:91], off offset:64
	global_store_dwordx2 v[108:109], v[86:87], off offset:256
	global_store_dwordx2 v[108:109], v[82:83], off offset:320
	global_load_dwordx4 v[82:85], v[110:111], off
	v_lshl_add_u64 v[86:87], v[148:149], 0, v[106:107]
	global_load_dwordx4 v[86:89], v[86:87], off
	v_mad_i64_i32 v[92:93], s[52:53], v175, s65, v[162:163]
	v_lshl_add_u64 v[92:93], v[92:93], 0, s[50:51]
	v_lshlrev_b32_e32 v90, 7, v174
	v_lshl_add_u64 v[92:93], v[92:93], 0, s[30:31]
	v_mov_b32_e32 v91, v147
	v_and_b32_e32 v90, 0x3e780, v90
	v_lshl_add_u64 v[92:93], v[92:93], 0, v[160:161]
	v_lshl_add_u64 v[94:95], v[150:151], 0, v[90:91]
	s_waitcnt vmcnt(1)
	v_pk_mul_f32 v[96:97], v[76:77], v[84:85]
	v_pk_mul_f32 v[98:99], v[74:75], v[82:83]
	v_pk_mul_f32 v[100:101], v[80:81], v[84:85]
	v_pk_mul_f32 v[102:103], v[78:79], v[82:83]
	v_pk_mul_f32 v[104:105], v[68:69], v[84:85]
	v_pk_mul_f32 v[106:107], v[66:67], v[82:83]
	v_pk_mul_f32 v[84:85], v[72:73], v[84:85]
	v_pk_mul_f32 v[82:83], v[70:71], v[82:83]
	s_waitcnt vmcnt(0)
	v_pk_fma_f32 v[80:81], v[80:81], v[88:89], v[96:97] neg_lo:[0,0,1] neg_hi:[0,0,1]
	v_pk_fma_f32 v[78:79], v[78:79], v[86:87], v[98:99] neg_lo:[0,0,1] neg_hi:[0,0,1]
	v_pk_fma_f32 v[76:77], v[76:77], v[88:89], v[100:101]
	v_pk_fma_f32 v[74:75], v[74:75], v[86:87], v[102:103]
	v_pk_fma_f32 v[72:73], v[72:73], v[88:89], v[104:105] neg_lo:[0,0,1] neg_hi:[0,0,1]
	v_pk_fma_f32 v[70:71], v[70:71], v[86:87], v[106:107] neg_lo:[0,0,1] neg_hi:[0,0,1]
	v_pk_fma_f32 v[68:69], v[68:69], v[88:89], v[84:85]
	v_pk_fma_f32 v[66:67], v[66:67], v[86:87], v[82:83]
	v_cvt_pk_bf16_f32 v78, v78, v79
	v_cvt_pk_bf16_f32 v79, v80, v81
	v_cvt_pk_bf16_f32 v74, v74, v75
	v_cvt_pk_bf16_f32 v75, v76, v77
	v_cvt_pk_bf16_f32 v70, v70, v71
	v_cvt_pk_bf16_f32 v71, v72, v73
	v_cvt_pk_bf16_f32 v66, v66, v67
	v_cvt_pk_bf16_f32 v67, v68, v69
	global_store_dwordx2 v[92:93], v[78:79], off
	global_store_dwordx2 v[92:93], v[74:75], off offset:64
	global_store_dwordx2 v[92:93], v[70:71], off offset:256
	global_store_dwordx2 v[92:93], v[66:67], off offset:320
	global_load_dwordx4 v[66:69], v[94:95], off
	v_lshl_add_u64 v[70:71], v[148:149], 0, v[90:91]
	global_load_dwordx4 v[70:73], v[70:71], off
	v_mad_i64_i32 v[76:77], s[52:53], v174, s65, v[162:163]
	v_lshl_add_u64 v[76:77], v[76:77], 0, s[50:51]
	v_lshlrev_b32_e32 v74, 7, v173
	v_lshl_add_u64 v[76:77], v[76:77], 0, s[30:31]
	v_mov_b32_e32 v75, v147
	v_and_b32_e32 v74, 0x3ef80, v74
	v_lshl_add_u64 v[76:77], v[76:77], 0, v[160:161]
	v_lshl_add_u64 v[78:79], v[150:151], 0, v[74:75]
	s_waitcnt vmcnt(1)
	v_pk_mul_f32 v[80:81], v[60:61], v[68:69]
	v_pk_mul_f32 v[82:83], v[58:59], v[66:67]
	v_pk_mul_f32 v[84:85], v[64:65], v[68:69]
	v_pk_mul_f32 v[86:87], v[62:63], v[66:67]
	v_pk_mul_f32 v[88:89], v[52:53], v[68:69]
	v_pk_mul_f32 v[90:91], v[50:51], v[66:67]
	v_pk_mul_f32 v[68:69], v[56:57], v[68:69]
	v_pk_mul_f32 v[66:67], v[54:55], v[66:67]
	s_waitcnt vmcnt(0)
	v_pk_fma_f32 v[64:65], v[64:65], v[72:73], v[80:81] neg_lo:[0,0,1] neg_hi:[0,0,1]
	v_pk_fma_f32 v[62:63], v[62:63], v[70:71], v[82:83] neg_lo:[0,0,1] neg_hi:[0,0,1]
	v_pk_fma_f32 v[60:61], v[60:61], v[72:73], v[84:85]
	v_pk_fma_f32 v[58:59], v[58:59], v[70:71], v[86:87]
	v_pk_fma_f32 v[56:57], v[56:57], v[72:73], v[88:89] neg_lo:[0,0,1] neg_hi:[0,0,1]
	v_pk_fma_f32 v[54:55], v[54:55], v[70:71], v[90:91] neg_lo:[0,0,1] neg_hi:[0,0,1]
	v_pk_fma_f32 v[52:53], v[52:53], v[72:73], v[68:69]
	v_pk_fma_f32 v[50:51], v[50:51], v[70:71], v[66:67]
	v_cvt_pk_bf16_f32 v62, v62, v63
	v_cvt_pk_bf16_f32 v63, v64, v65
	v_cvt_pk_bf16_f32 v58, v58, v59
	v_cvt_pk_bf16_f32 v59, v60, v61
	v_cvt_pk_bf16_f32 v54, v54, v55
	v_cvt_pk_bf16_f32 v55, v56, v57
	v_cvt_pk_bf16_f32 v50, v50, v51
	v_cvt_pk_bf16_f32 v51, v52, v53
	global_store_dwordx2 v[76:77], v[62:63], off
	global_store_dwordx2 v[76:77], v[58:59], off offset:64
	global_store_dwordx2 v[76:77], v[54:55], off offset:256
	global_store_dwordx2 v[76:77], v[50:51], off offset:320
	global_load_dwordx4 v[50:53], v[78:79], off
	v_lshl_add_u64 v[54:55], v[148:149], 0, v[74:75]
	global_load_dwordx4 v[54:57], v[54:55], off
	v_mad_i64_i32 v[60:61], s[52:53], v173, s65, v[162:163]
	v_lshl_add_u64 v[60:61], v[60:61], 0, s[50:51]
	v_lshlrev_b32_e32 v58, 7, v172
	v_lshl_add_u64 v[60:61], v[60:61], 0, s[30:31]
	v_mov_b32_e32 v59, v147
	v_and_b32_e32 v58, 0x3f780, v58
	v_lshl_add_u64 v[60:61], v[60:61], 0, v[160:161]
	v_lshl_add_u64 v[62:63], v[150:151], 0, v[58:59]
	s_waitcnt vmcnt(1)
; DI unsigned pk2(float lo, float hi) { const f32x2 v = {lo, hi}; const bf16x2_t b = __builtin_convertvector(v, bf16x2_t); return __builtin_bit_cast(unsigned, b); }
;     DI void operator()(const Acc& acc, const Unit& u, int wr, int wc, int fr, int fq) const {
;         const int row0 = u.pm * 256 + wr * 64 + fr;
;         if (u.pn < 7) {
;             const int jj = 16 * (wc & 1) + 4 * fq;
; #pragma unroll
;             for (int ai = 0; ai < 2; ++ai)
; #pragma unroll
;                 for (int m = 0; m < 4; ++m) {
;                     const int r = row0 + ai * 128 + m * 16; const int pos = r & (SEQ - 1);
;                     const f32x4 c = *(const f32x4*)(ropec + pos * 32 + jj), s = *(const f32x4*)(ropes + pos * 32 + jj);
; #pragma unroll
;                     for (int bj = 0; bj < 2; ++bj) {
;                         const f32x4 x1 = acc[ai][bj][m][0], x2 = acc[ai][bj][m][1];
;                         const f32x4 o1 = x1 * c - x2 * s, o2 = x1 * s + x2 * c;
;                         bf16_t* p = Z + (size_t)r * NZ + u.pn * 256 + bj * 128 + (wc >> 1) * 64 + jj;
;                         u32x2 w1; w1.x = pk2(o1[0], o1[1]); w1.y = pk2(o1[2], o1[3]);
;                         u32x2 w2; w2.x = pk2(o2[0], o2[1]); w2.y = pk2(o2[2], o2[3]);
;                         *(u32x2*)p = w1; *(u32x2*)(p + 32) = w2;
;                     }
;                 }
	v_pk_mul_f32 v[64:65], v[44:45], v[52:53]
	v_pk_mul_f32 v[66:67], v[42:43], v[50:51]
	v_pk_mul_f32 v[68:69], v[48:49], v[52:53]
	v_pk_mul_f32 v[70:71], v[46:47], v[50:51]
	v_pk_mul_f32 v[72:73], v[36:37], v[52:53]
	v_pk_mul_f32 v[74:75], v[34:35], v[50:51]
	v_pk_mul_f32 v[52:53], v[40:41], v[52:53]
	v_pk_mul_f32 v[50:51], v[38:39], v[50:51]
	s_waitcnt vmcnt(0)
	v_pk_fma_f32 v[48:49], v[48:49], v[56:57], v[64:65] neg_lo:[0,0,1] neg_hi:[0,0,1]
	v_pk_fma_f32 v[46:47], v[46:47], v[54:55], v[66:67] neg_lo:[0,0,1] neg_hi:[0,0,1]
	v_pk_fma_f32 v[44:45], v[44:45], v[56:57], v[68:69]
	v_pk_fma_f32 v[42:43], v[42:43], v[54:55], v[70:71]
	v_pk_fma_f32 v[40:41], v[40:41], v[56:57], v[72:73] neg_lo:[0,0,1] neg_hi:[0,0,1]
	v_pk_fma_f32 v[38:39], v[38:39], v[54:55], v[74:75] neg_lo:[0,0,1] neg_hi:[0,0,1]
	v_pk_fma_f32 v[36:37], v[36:37], v[56:57], v[52:53]
	v_pk_fma_f32 v[34:35], v[34:35], v[54:55], v[50:51]
	v_cvt_pk_bf16_f32 v46, v46, v47
	v_cvt_pk_bf16_f32 v47, v48, v49
	v_cvt_pk_bf16_f32 v42, v42, v43
	v_cvt_pk_bf16_f32 v43, v44, v45
	v_cvt_pk_bf16_f32 v38, v38, v39
	v_cvt_pk_bf16_f32 v39, v40, v41
	v_cvt_pk_bf16_f32 v34, v34, v35
	v_cvt_pk_bf16_f32 v35, v36, v37
	global_store_dwordx2 v[60:61], v[46:47], off
	global_store_dwordx2 v[60:61], v[42:43], off offset:64
	global_store_dwordx2 v[60:61], v[38:39], off offset:256
	global_store_dwordx2 v[60:61], v[34:35], off offset:320
	global_load_dwordx4 v[34:37], v[62:63], off
	v_lshl_add_u64 v[38:39], v[148:149], 0, v[58:59]
	global_load_dwordx4 v[38:41], v[38:39], off
	v_mad_i64_i32 v[44:45], s[52:53], v172, s65, v[162:163]
	v_lshl_add_u64 v[44:45], v[44:45], 0, s[50:51]
	v_lshlrev_b32_e32 v42, 7, v171
	v_lshl_add_u64 v[44:45], v[44:45], 0, s[30:31]
	v_mov_b32_e32 v43, v147
	v_and_b32_e32 v42, 0x3ff80, v42
	v_lshl_add_u64 v[44:45], v[44:45], 0, v[160:161]
	v_lshl_add_u64 v[46:47], v[150:151], 0, v[42:43]
	s_waitcnt vmcnt(1)
	v_pk_mul_f32 v[48:49], v[28:29], v[36:37]
	v_pk_mul_f32 v[50:51], v[26:27], v[34:35]
	v_pk_mul_f32 v[52:53], v[32:33], v[36:37]
	v_pk_mul_f32 v[54:55], v[30:31], v[34:35]
	v_pk_mul_f32 v[56:57], v[20:21], v[36:37]
	v_pk_mul_f32 v[58:59], v[18:19], v[34:35]
	v_pk_mul_f32 v[36:37], v[24:25], v[36:37]
	v_pk_mul_f32 v[34:35], v[22:23], v[34:35]
	s_waitcnt vmcnt(0)
	v_pk_fma_f32 v[32:33], v[32:33], v[40:41], v[48:49] neg_lo:[0,0,1] neg_hi:[0,0,1]
	v_pk_fma_f32 v[30:31], v[30:31], v[38:39], v[50:51] neg_lo:[0,0,1] neg_hi:[0,0,1]
	v_pk_fma_f32 v[28:29], v[28:29], v[40:41], v[52:53]
	v_pk_fma_f32 v[26:27], v[26:27], v[38:39], v[54:55]
	v_pk_fma_f32 v[24:25], v[24:25], v[40:41], v[56:57] neg_lo:[0,0,1] neg_hi:[0,0,1]
	v_pk_fma_f32 v[22:23], v[22:23], v[38:39], v[58:59] neg_lo:[0,0,1] neg_hi:[0,0,1]
	v_pk_fma_f32 v[20:21], v[20:21], v[40:41], v[36:37]
	v_pk_fma_f32 v[18:19], v[18:19], v[38:39], v[34:35]
	v_cvt_pk_bf16_f32 v30, v30, v31
	v_cvt_pk_bf16_f32 v31, v32, v33
	v_cvt_pk_bf16_f32 v26, v26, v27
	v_cvt_pk_bf16_f32 v27, v28, v29
	v_cvt_pk_bf16_f32 v22, v22, v23
	v_cvt_pk_bf16_f32 v23, v24, v25
	v_cvt_pk_bf16_f32 v18, v18, v19
	v_cvt_pk_bf16_f32 v19, v20, v21
	global_store_dwordx2 v[44:45], v[30:31], off
	global_store_dwordx2 v[44:45], v[26:27], off offset:64
	global_store_dwordx2 v[44:45], v[22:23], off offset:256
	global_store_dwordx2 v[44:45], v[18:19], off offset:320
	global_load_dwordx4 v[18:21], v[46:47], off
	v_lshl_add_u64 v[22:23], v[148:149], 0, v[42:43]
	global_load_dwordx4 v[22:25], v[22:23], off
	v_mad_i64_i32 v[26:27], s[52:53], v171, s65, v[162:163]
	v_lshl_add_u64 v[26:27], v[26:27], 0, s[50:51]
	v_lshl_add_u64 v[26:27], v[26:27], 0, s[30:31]
	v_lshl_add_u64 v[26:27], v[26:27], 0, v[160:161]
	s_waitcnt vmcnt(1)
	v_pk_mul_f32 v[28:29], v[12:13], v[20:21]
	v_pk_mul_f32 v[30:31], v[10:11], v[18:19]
	v_pk_mul_f32 v[32:33], v[16:17], v[20:21]
	v_pk_mul_f32 v[34:35], v[14:15], v[18:19]
	v_pk_mul_f32 v[36:37], v[4:5], v[20:21]
	v_pk_mul_f32 v[38:39], v[2:3], v[18:19]
	v_pk_mul_f32 v[20:21], v[8:9], v[20:21]
	v_pk_mul_f32 v[18:19], v[6:7], v[18:19]
	s_waitcnt vmcnt(0)
	v_pk_fma_f32 v[16:17], v[16:17], v[24:25], v[28:29] neg_lo:[0,0,1] neg_hi:[0,0,1]
	v_pk_fma_f32 v[14:15], v[14:15], v[22:23], v[30:31] neg_lo:[0,0,1] neg_hi:[0,0,1]
	v_pk_fma_f32 v[12:13], v[12:13], v[24:25], v[32:33]
	v_pk_fma_f32 v[10:11], v[10:11], v[22:23], v[34:35]
	v_pk_fma_f32 v[8:9], v[8:9], v[24:25], v[36:37] neg_lo:[0,0,1] neg_hi:[0,0,1]
	v_pk_fma_f32 v[6:7], v[6:7], v[22:23], v[38:39] neg_lo:[0,0,1] neg_hi:[0,0,1]
	v_pk_fma_f32 v[4:5], v[4:5], v[24:25], v[20:21]
	v_pk_fma_f32 v[2:3], v[2:3], v[22:23], v[18:19]
	v_cvt_pk_bf16_f32 v14, v14, v15
	v_cvt_pk_bf16_f32 v15, v16, v17
	v_cvt_pk_bf16_f32 v10, v10, v11
	v_cvt_pk_bf16_f32 v11, v12, v13
	v_cvt_pk_bf16_f32 v6, v6, v7
	v_cvt_pk_bf16_f32 v7, v8, v9
	v_cvt_pk_bf16_f32 v2, v2, v3
	v_cvt_pk_bf16_f32 v3, v4, v5
	global_store_dwordx2 v[26:27], v[14:15], off
	global_store_dwordx2 v[26:27], v[10:11], off offset:64
	global_store_dwordx2 v[26:27], v[6:7], off offset:256
	global_store_dwordx2 v[26:27], v[2:3], off offset:320
	s_andn2_b64 vcc, exec, s[4:5]
	s_mov_b64 s[4:5], -1
	s_cbranch_vccnz .LBB0_229
